# MLA attention main loop: LDS fragment reads streamed 8 ahead with counted lgkmcnt (same math)
# speedup vs baseline: 1.0175x; 1.0175x over previous
.LBB0_562:
	s_mul_i32 s0, s22, 0xa000
	v_add_u32_e32 v204, s0, v178
	v_add_u32_e32 v205, s0, v180
	v_add_u32_e32 v189, s0, v181
	v_add_u32_e32 v188, s0, v182
	ds_read_b128 v[208:211], v204
	ds_read_b128 v[212:215], v205
	ds_read_b128 v[216:219], v189
	ds_read_b128 v[220:223], v188
	v_add_u32_e32 v199, s0, v184
	v_add_u32_e32 v200, s0, v185
	v_add_u32_e32 v201, s0, v186
	v_add_u32_e32 v207, s0, v187
	ds_read_b128 v[224:227], v204 offset:128
	ds_read_b128 v[228:231], v205 offset:128
	ds_read_b128 v[232:235], v189 offset:128
	ds_read_b128 v[236:239], v188 offset:128
	s_waitcnt lgkmcnt(7)
	v_mfma_f32_32x32x16_bf16 v[96:111], v[208:211], v[112:115], v[64:79]
	ds_read_b128 v[240:243], v204 offset:256
	s_waitcnt lgkmcnt(7)
	v_mfma_f32_32x32x16_bf16 v[96:111], v[212:215], v[116:119], v[96:111]
	ds_read_b128 v[248:251], v205 offset:256
	s_waitcnt lgkmcnt(7)
	v_mfma_f32_32x32x16_bf16 v[96:111], v[216:219], v[120:123], v[96:111]
	ds_read_b128 v[208:211], v189 offset:256
	s_waitcnt lgkmcnt(7)
	v_mfma_f32_32x32x16_bf16 v[96:111], v[220:223], v[124:127], v[96:111]
	ds_read_b128 v[212:215], v188 offset:256
	s_waitcnt lgkmcnt(7)
	v_mfma_f32_32x32x16_bf16 v[96:111], v[224:227], v[128:131], v[96:111]
	ds_read_b128 v[216:219], v199 offset:24576
	s_waitcnt lgkmcnt(7)
	v_mfma_f32_32x32x16_bf16 v[96:111], v[228:231], v[132:135], v[96:111]
	ds_read_b128 v[220:223], v199 offset:28672
	s_waitcnt lgkmcnt(7)
	v_mfma_f32_32x32x16_bf16 v[96:111], v[232:235], v[136:139], v[96:111]
	ds_read_b128 v[224:227], v199 offset:32768
	s_waitcnt lgkmcnt(7)
	v_mfma_f32_32x32x16_bf16 v[96:111], v[236:239], v[140:143], v[96:111]
	ds_read_b128 v[228:231], v199 offset:36864
	s_waitcnt lgkmcnt(7)
	v_mfma_f32_32x32x16_bf16 v[96:111], v[240:243], v[144:147], v[96:111]
	ds_read_b128 v[232:235], v200 offset:24576
	s_waitcnt lgkmcnt(7)
	v_mfma_f32_32x32x16_bf16 v[96:111], v[248:251], v[148:151], v[96:111]
	ds_read_b128 v[236:239], v200 offset:28672
	s_waitcnt lgkmcnt(7)
	v_mfma_f32_32x32x16_bf16 v[96:111], v[208:211], v[152:155], v[96:111]
	ds_read_b128 v[240:243], v200 offset:32768
	s_waitcnt lgkmcnt(7)
	v_mfma_f32_32x32x16_bf16 v[96:111], v[212:215], v[156:159], v[96:111]
	ds_read_b128 v[248:251], v200 offset:36864
	s_add_i32 s0, s22, 1
	s_cmp_lg_u32 s22, 2
	s_cselect_b32 s22, s0, 0
	s_add_i32 s0, s15, 1
	s_cmp_lg_u32 s15, 2
	s_cselect_b32 s15, s0, 0
	s_nop 4
	v_max_f32_e32 v80, v97, v97
	v_max_f32_e32 v81, v96, v96
	v_max_f32_e32 v80, v81, v80
	v_max3_f32 v80, v80, v98, v99
	v_max3_f32 v80, v80, v100, v101
	v_max3_f32 v80, v80, v102, v103
	v_max3_f32 v80, v80, v104, v105
	v_max3_f32 v80, v80, v106, v107
	v_max3_f32 v80, v80, v108, v109
	v_max3_f32 v206, v80, v110, v111
	v_cmp_ge_f32_e32 vcc, s85, v206
	s_cmp_eq_u64 vcc, exec
	s_cbranch_scc1 .Lmla_a_norescale
	ds_bpermute_b32 v64, v183, v206
	s_waitcnt lgkmcnt(0)
	v_max3_f32 v64, v206, v64, 0
	v_exp_f32_e64 v66, -v64
	v_add_f32_e32 v165, v165, v64
	v_xor_b32_e32 v80, 0x80000000, v165
	v_pk_add_f32 v[96:97], v[96:97], v[64:65] op_sel_hi:[1,0] neg_lo:[0,1] neg_hi:[0,1]
	v_mul_f32_e32 v164, v164, v66
	v_pk_mul_f32 v[14:15], v[14:15], v[66:67] op_sel_hi:[1,0]
	v_pk_mul_f32 v[12:13], v[12:13], v[66:67] op_sel_hi:[1,0]
	v_pk_mul_f32 v[10:11], v[10:11], v[66:67] op_sel_hi:[1,0]
	v_pk_mul_f32 v[8:9], v[8:9], v[66:67] op_sel_hi:[1,0]
	v_pk_mul_f32 v[6:7], v[6:7], v[66:67] op_sel_hi:[1,0]
	v_pk_mul_f32 v[4:5], v[4:5], v[66:67] op_sel_hi:[1,0]
	v_pk_mul_f32 v[2:3], v[2:3], v[66:67] op_sel_hi:[1,0]
	v_pk_mul_f32 v[0:1], v[0:1], v[66:67] op_sel_hi:[1,0]
	v_pk_mul_f32 v[30:31], v[30:31], v[66:67] op_sel_hi:[1,0]
	v_pk_mul_f32 v[28:29], v[28:29], v[66:67] op_sel_hi:[1,0]
	v_pk_mul_f32 v[26:27], v[26:27], v[66:67] op_sel_hi:[1,0]
	v_pk_mul_f32 v[24:25], v[24:25], v[66:67] op_sel_hi:[1,0]
	v_pk_mul_f32 v[22:23], v[22:23], v[66:67] op_sel_hi:[1,0]
	v_pk_mul_f32 v[20:21], v[20:21], v[66:67] op_sel_hi:[1,0]
	v_pk_mul_f32 v[18:19], v[18:19], v[66:67] op_sel_hi:[1,0]
	v_pk_mul_f32 v[16:17], v[16:17], v[66:67] op_sel_hi:[1,0]
	v_pk_mul_f32 v[46:47], v[46:47], v[66:67] op_sel_hi:[1,0]
	v_pk_mul_f32 v[44:45], v[44:45], v[66:67] op_sel_hi:[1,0]
	v_pk_mul_f32 v[42:43], v[42:43], v[66:67] op_sel_hi:[1,0]
	v_pk_mul_f32 v[40:41], v[40:41], v[66:67] op_sel_hi:[1,0]
	v_pk_mul_f32 v[38:39], v[38:39], v[66:67] op_sel_hi:[1,0]
	v_pk_mul_f32 v[36:37], v[36:37], v[66:67] op_sel_hi:[1,0]
	v_pk_mul_f32 v[34:35], v[34:35], v[66:67] op_sel_hi:[1,0]
	v_pk_mul_f32 v[32:33], v[32:33], v[66:67] op_sel_hi:[1,0]
	v_pk_mul_f32 v[62:63], v[62:63], v[66:67] op_sel_hi:[1,0]
	v_pk_mul_f32 v[60:61], v[60:61], v[66:67] op_sel_hi:[1,0]
	v_pk_mul_f32 v[58:59], v[58:59], v[66:67] op_sel_hi:[1,0]
	v_pk_mul_f32 v[56:57], v[56:57], v[66:67] op_sel_hi:[1,0]
	v_pk_mul_f32 v[54:55], v[54:55], v[66:67] op_sel_hi:[1,0]
	v_pk_mul_f32 v[52:53], v[52:53], v[66:67] op_sel_hi:[1,0]
	v_pk_mul_f32 v[50:51], v[50:51], v[66:67] op_sel_hi:[1,0]
	v_pk_mul_f32 v[48:49], v[48:49], v[66:67] op_sel_hi:[1,0]
	v_pk_add_f32 v[98:99], v[98:99], v[64:65] op_sel_hi:[1,0] neg_lo:[0,1] neg_hi:[0,1]
	v_pk_add_f32 v[100:101], v[100:101], v[64:65] op_sel_hi:[1,0] neg_lo:[0,1] neg_hi:[0,1]
	v_pk_add_f32 v[102:103], v[102:103], v[64:65] op_sel_hi:[1,0] neg_lo:[0,1] neg_hi:[0,1]
	v_pk_add_f32 v[104:105], v[104:105], v[64:65] op_sel_hi:[1,0] neg_lo:[0,1] neg_hi:[0,1]
	v_pk_add_f32 v[106:107], v[106:107], v[64:65] op_sel_hi:[1,0] neg_lo:[0,1] neg_hi:[0,1]
	v_pk_add_f32 v[108:109], v[108:109], v[64:65] op_sel_hi:[1,0] neg_lo:[0,1] neg_hi:[0,1]
	v_pk_add_f32 v[110:111], v[110:111], v[64:65] op_sel_hi:[1,0] neg_lo:[0,1] neg_hi:[0,1]
	v_mov_b32_e32 v64, v80
	v_mov_b32_e32 v65, v80
	v_mov_b32_e32 v66, v80
	v_mov_b32_e32 v67, v80
	v_mov_b32_e32 v68, v80
	v_mov_b32_e32 v69, v80
	v_mov_b32_e32 v70, v80
	v_mov_b32_e32 v71, v80
	v_mov_b32_e32 v72, v80
	v_mov_b32_e32 v73, v80
	v_mov_b32_e32 v74, v80
	v_mov_b32_e32 v75, v80
	v_mov_b32_e32 v76, v80
	v_mov_b32_e32 v77, v80
	v_mov_b32_e32 v78, v80
	v_mov_b32_e32 v79, v80
.Lmla_a_norescale:
	v_exp_f32_e32 v96, v96
	v_exp_f32_e32 v97, v97
	v_exp_f32_e32 v98, v98
	v_exp_f32_e32 v99, v99
	v_add_f32_e32 v192, 0, v96
	v_exp_f32_e32 v193, v100
	v_add_f32_e32 v192, v97, v192
	v_add_f32_e32 v192, v98, v192
	v_add_f32_e32 v192, v99, v192
	v_exp_f32_e32 v101, v101
	v_add_f32_e32 v100, v193, v192
	v_exp_f32_e32 v192, v102
	v_exp_f32_e32 v194, v103
	v_exp_f32_e32 v195, v104
	v_add_f32_e32 v100, v101, v100
	v_exp_f32_e32 v198, v105
	v_add_f32_e32 v100, v192, v100
	v_exp_f32_e32 v106, v106
	v_add_f32_e32 v100, v194, v100
	v_exp_f32_e32 v107, v107
	v_add_f32_e32 v100, v195, v100
	v_exp_f32_e32 v108, v108
	v_add_f32_e32 v100, v198, v100
	v_exp_f32_e32 v109, v109
	v_add_f32_e32 v100, v106, v100
	v_add_f32_e32 v100, v107, v100
	v_add_f32_e32 v100, v108, v100
	v_cvt_pk_bf16_f32 v104, v193, v101
	v_add_f32_e32 v100, v109, v100
	v_cvt_pk_bf16_f32 v102, v96, v97
	v_cvt_pk_bf16_f32 v103, v98, v99
	v_cvt_pk_bf16_f32 v97, v106, v107
	v_cvt_pk_bf16_f32 v98, v108, v109
	v_cvt_pk_bf16_f32 v105, v192, v194
	v_exp_f32_e32 v110, v110
	v_exp_f32_e32 v111, v111
	v_cvt_pk_bf16_f32 v96, v195, v198
	v_cvt_pk_bf16_f32 v99, v110, v111
	v_add_f32_e32 v100, v110, v100
	v_add_f32_e32 v100, v111, v100
	s_waitcnt lgkmcnt(7)
	v_mfma_f32_32x32x16_bf16 v[48:63], v[216:219], v[102:105], v[48:63]
	ds_read_b128 v[208:211], v204 offset:12288
	s_waitcnt lgkmcnt(7)
	v_mfma_f32_32x32x16_bf16 v[32:47], v[220:223], v[102:105], v[32:47]
	ds_read_b128 v[212:215], v205 offset:12288
	s_waitcnt lgkmcnt(7)
	v_mfma_f32_32x32x16_bf16 v[16:31], v[224:227], v[102:105], v[16:31]
	ds_read_b128 v[216:219], v189 offset:12288
	s_waitcnt lgkmcnt(7)
	v_mfma_f32_32x32x16_bf16 v[0:15], v[228:231], v[102:105], v[0:15]
	ds_read_b128 v[220:223], v188 offset:12288
	s_waitcnt lgkmcnt(7)
	v_mfma_f32_32x32x16_bf16 v[48:63], v[232:235], v[96:99], v[48:63]
	ds_read_b128 v[224:227], v204 offset:12416
	s_waitcnt lgkmcnt(7)
	v_mfma_f32_32x32x16_bf16 v[32:47], v[236:239], v[96:99], v[32:47]
	ds_read_b128 v[228:231], v205 offset:12416
	s_waitcnt lgkmcnt(7)
	v_mfma_f32_32x32x16_bf16 v[16:31], v[240:243], v[96:99], v[16:31]
	ds_read_b128 v[232:235], v189 offset:12416
	s_waitcnt lgkmcnt(7)
	v_mfma_f32_32x32x16_bf16 v[0:15], v[248:251], v[96:99], v[0:15]
	ds_read_b128 v[236:239], v188 offset:12416
	s_waitcnt lgkmcnt(7)
	v_mfma_f32_32x32x16_bf16 v[80:95], v[208:211], v[112:115], v[64:79]
	ds_read_b128 v[240:243], v204 offset:12544
	s_waitcnt lgkmcnt(7)
	v_mfma_f32_32x32x16_bf16 v[80:95], v[212:215], v[116:119], v[80:95]
	ds_read_b128 v[248:251], v205 offset:12544
	s_waitcnt lgkmcnt(7)
	v_mfma_f32_32x32x16_bf16 v[80:95], v[216:219], v[120:123], v[80:95]
	ds_read_b128 v[208:211], v189 offset:12544
	s_waitcnt lgkmcnt(7)
	v_mfma_f32_32x32x16_bf16 v[80:95], v[220:223], v[124:127], v[80:95]
	ds_read_b128 v[212:215], v188 offset:12544
	s_waitcnt lgkmcnt(7)
	v_mfma_f32_32x32x16_bf16 v[80:95], v[224:227], v[128:131], v[80:95]
	ds_read_b128 v[216:219], v201 offset:24576
	s_waitcnt lgkmcnt(7)
	v_mfma_f32_32x32x16_bf16 v[80:95], v[228:231], v[132:135], v[80:95]
	ds_read_b128 v[220:223], v201 offset:28672
	s_waitcnt lgkmcnt(7)
	v_mfma_f32_32x32x16_bf16 v[80:95], v[232:235], v[136:139], v[80:95]
	ds_read_b128 v[224:227], v201 offset:32768
	s_waitcnt lgkmcnt(7)
	v_mfma_f32_32x32x16_bf16 v[80:95], v[236:239], v[140:143], v[80:95]
	ds_read_b128 v[228:231], v201 offset:36864
	s_waitcnt lgkmcnt(7)
	v_mfma_f32_32x32x16_bf16 v[80:95], v[240:243], v[144:147], v[80:95]
	ds_read_b128 v[232:235], v207 offset:24576
	s_waitcnt lgkmcnt(7)
	v_mfma_f32_32x32x16_bf16 v[80:95], v[248:251], v[148:151], v[80:95]
	ds_read_b128 v[236:239], v207 offset:28672
	s_waitcnt lgkmcnt(7)
	v_mfma_f32_32x32x16_bf16 v[80:95], v[208:211], v[152:155], v[80:95]
	ds_read_b128 v[240:243], v207 offset:32768
	s_waitcnt lgkmcnt(7)
	v_mfma_f32_32x32x16_bf16 v[80:95], v[212:215], v[156:159], v[80:95]
	ds_read_b128 v[248:251], v207 offset:36864
	v_lshl_add_u64 v[166:167], v[166:167], 0, s[66:67]
	v_lshl_add_u64 v[168:169], v[168:169], 0, v[162:163]
	v_lshl_add_u64 v[170:171], v[170:171], 0, v[160:161]
	v_lshl_add_u64 v[172:173], v[172:173], 0, v[176:177]
	s_nop 7
	v_max_f32_e32 v96, v81, v81
	v_max_f32_e32 v97, v80, v80
	v_max_f32_e32 v96, v97, v96
	v_max3_f32 v96, v96, v82, v83
	v_max3_f32 v96, v96, v84, v85
	v_max3_f32 v96, v96, v86, v87
	v_max3_f32 v96, v96, v88, v89
	v_max3_f32 v96, v96, v90, v91
	v_max3_f32 v96, v96, v92, v93
	v_max3_f32 v97, v96, v94, v95
	v_cmp_ge_f32_e32 vcc, s85, v97
	v_add_f32_e32 v96, v164, v100
	s_cmp_eq_u64 vcc, exec
	s_cbranch_scc1 .Lmla_b_norescale
	ds_bpermute_b32 v64, v183, v97
	s_waitcnt lgkmcnt(0)
	v_max3_f32 v66, v97, v64, 0
	v_exp_f32_e64 v68, -v66
	v_add_f32_e32 v165, v165, v66
	v_xor_b32_e32 v64, 0x80000000, v165
	v_pk_add_f32 v[80:81], v[80:81], v[66:67] op_sel_hi:[1,0] neg_lo:[0,1] neg_hi:[0,1]
	v_pk_mul_f32 v[62:63], v[62:63], v[68:69] op_sel_hi:[1,0]
	v_pk_mul_f32 v[60:61], v[60:61], v[68:69] op_sel_hi:[1,0]
	v_pk_mul_f32 v[58:59], v[58:59], v[68:69] op_sel_hi:[1,0]
	v_pk_mul_f32 v[56:57], v[56:57], v[68:69] op_sel_hi:[1,0]
	v_pk_mul_f32 v[54:55], v[54:55], v[68:69] op_sel_hi:[1,0]
	v_pk_mul_f32 v[52:53], v[52:53], v[68:69] op_sel_hi:[1,0]
	v_pk_mul_f32 v[50:51], v[50:51], v[68:69] op_sel_hi:[1,0]
	v_pk_mul_f32 v[48:49], v[48:49], v[68:69] op_sel_hi:[1,0]
	v_pk_mul_f32 v[46:47], v[46:47], v[68:69] op_sel_hi:[1,0]
	v_pk_mul_f32 v[44:45], v[44:45], v[68:69] op_sel_hi:[1,0]
	v_pk_mul_f32 v[42:43], v[42:43], v[68:69] op_sel_hi:[1,0]
	v_pk_mul_f32 v[40:41], v[40:41], v[68:69] op_sel_hi:[1,0]
	v_pk_mul_f32 v[38:39], v[38:39], v[68:69] op_sel_hi:[1,0]
	v_pk_mul_f32 v[36:37], v[36:37], v[68:69] op_sel_hi:[1,0]
	v_pk_mul_f32 v[34:35], v[34:35], v[68:69] op_sel_hi:[1,0]
	v_pk_mul_f32 v[32:33], v[32:33], v[68:69] op_sel_hi:[1,0]
	v_pk_mul_f32 v[30:31], v[30:31], v[68:69] op_sel_hi:[1,0]
	v_pk_mul_f32 v[28:29], v[28:29], v[68:69] op_sel_hi:[1,0]
	v_pk_mul_f32 v[26:27], v[26:27], v[68:69] op_sel_hi:[1,0]
	v_pk_mul_f32 v[24:25], v[24:25], v[68:69] op_sel_hi:[1,0]
	v_pk_mul_f32 v[22:23], v[22:23], v[68:69] op_sel_hi:[1,0]
	v_pk_mul_f32 v[20:21], v[20:21], v[68:69] op_sel_hi:[1,0]
	v_pk_mul_f32 v[18:19], v[18:19], v[68:69] op_sel_hi:[1,0]
	v_pk_mul_f32 v[16:17], v[16:17], v[68:69] op_sel_hi:[1,0]
	v_pk_mul_f32 v[14:15], v[14:15], v[68:69] op_sel_hi:[1,0]
	v_pk_mul_f32 v[12:13], v[12:13], v[68:69] op_sel_hi:[1,0]
	v_pk_mul_f32 v[10:11], v[10:11], v[68:69] op_sel_hi:[1,0]
	v_pk_mul_f32 v[8:9], v[8:9], v[68:69] op_sel_hi:[1,0]
	v_pk_mul_f32 v[6:7], v[6:7], v[68:69] op_sel_hi:[1,0]
	v_pk_mul_f32 v[4:5], v[4:5], v[68:69] op_sel_hi:[1,0]
	v_pk_mul_f32 v[2:3], v[2:3], v[68:69] op_sel_hi:[1,0]
	v_pk_mul_f32 v[0:1], v[0:1], v[68:69] op_sel_hi:[1,0]
	v_pk_add_f32 v[82:83], v[82:83], v[66:67] op_sel_hi:[1,0] neg_lo:[0,1] neg_hi:[0,1]
	v_pk_add_f32 v[84:85], v[84:85], v[66:67] op_sel_hi:[1,0] neg_lo:[0,1] neg_hi:[0,1]
	v_pk_add_f32 v[86:87], v[86:87], v[66:67] op_sel_hi:[1,0] neg_lo:[0,1] neg_hi:[0,1]
	v_pk_add_f32 v[88:89], v[88:89], v[66:67] op_sel_hi:[1,0] neg_lo:[0,1] neg_hi:[0,1]
	v_pk_add_f32 v[90:91], v[90:91], v[66:67] op_sel_hi:[1,0] neg_lo:[0,1] neg_hi:[0,1]
	v_pk_add_f32 v[92:93], v[92:93], v[66:67] op_sel_hi:[1,0] neg_lo:[0,1] neg_hi:[0,1]
	v_pk_add_f32 v[94:95], v[94:95], v[66:67] op_sel_hi:[1,0] neg_lo:[0,1] neg_hi:[0,1]
	v_mul_f32_e32 v96, v96, v68
	v_mov_b32_e32 v65, v64
	v_mov_b32_e32 v66, v64
	v_mov_b32_e32 v67, v64
	v_mov_b32_e32 v68, v64
	v_mov_b32_e32 v69, v64
	v_mov_b32_e32 v70, v64
	v_mov_b32_e32 v71, v64
	v_mov_b32_e32 v72, v64
	v_mov_b32_e32 v73, v64
	v_mov_b32_e32 v74, v64
	v_mov_b32_e32 v75, v64
	v_mov_b32_e32 v76, v64
	v_mov_b32_e32 v77, v64
	v_mov_b32_e32 v78, v64
	v_mov_b32_e32 v79, v64
.Lmla_b_norescale:
	v_exp_f32_e32 v80, v80
	v_exp_f32_e32 v81, v81
	v_exp_f32_e32 v82, v82
	v_exp_f32_e32 v83, v83
	v_add_f32_e32 v97, 0, v80
	v_exp_f32_e32 v98, v84
	v_add_f32_e32 v97, v81, v97
	v_add_f32_e32 v97, v82, v97
	v_add_f32_e32 v97, v83, v97
	v_add_f32_e32 v84, v98, v97
	v_exp_f32_e32 v97, v85
	v_exp_f32_e32 v99, v86
	v_exp_f32_e32 v87, v87
	v_exp_f32_e32 v88, v88
	v_add_f32_e32 v84, v97, v84
	v_exp_f32_e32 v89, v89
	v_add_f32_e32 v84, v99, v84
	v_exp_f32_e32 v90, v90
	v_add_f32_e32 v84, v87, v84
	v_exp_f32_e32 v91, v91
	v_add_f32_e32 v84, v88, v84
	v_exp_f32_e32 v92, v92
	v_add_f32_e32 v84, v89, v84
	v_exp_f32_e32 v93, v93
	v_add_f32_e32 v84, v90, v84
	v_exp_f32_e32 v94, v94
	v_add_f32_e32 v84, v91, v84
	v_exp_f32_e32 v95, v95
	v_add_f32_e32 v84, v92, v84
	v_add_f32_e32 v84, v93, v84
	v_add_f32_e32 v84, v94, v84
	v_cvt_pk_bf16_f32 v85, v82, v83
	v_cvt_pk_bf16_f32 v82, v92, v93
	v_add_f32_e32 v100, v95, v84
	v_cvt_pk_bf16_f32 v84, v80, v81
	v_cvt_pk_bf16_f32 v80, v88, v89
	v_cvt_pk_bf16_f32 v81, v90, v91
	v_cvt_pk_bf16_f32 v86, v98, v97
	v_cvt_pk_bf16_f32 v87, v99, v87
	v_cvt_pk_bf16_f32 v83, v94, v95
	v_add_f32_e32 v164, v96, v100
	s_waitcnt lgkmcnt(7)
	v_mfma_f32_32x32x16_bf16 v[48:63], v[216:219], v[84:87], v[48:63]
	s_waitcnt lgkmcnt(6)
	v_mfma_f32_32x32x16_bf16 v[32:47], v[220:223], v[84:87], v[32:47]
	s_waitcnt lgkmcnt(5)
	v_mfma_f32_32x32x16_bf16 v[16:31], v[224:227], v[84:87], v[16:31]
	s_waitcnt lgkmcnt(4)
	v_mfma_f32_32x32x16_bf16 v[0:15], v[228:231], v[84:87], v[0:15]
	s_waitcnt lgkmcnt(3)
	v_mfma_f32_32x32x16_bf16 v[48:63], v[232:235], v[80:83], v[48:63]
	s_waitcnt lgkmcnt(2)
	v_mfma_f32_32x32x16_bf16 v[32:47], v[236:239], v[80:83], v[32:47]
	s_waitcnt lgkmcnt(1)
	v_mfma_f32_32x32x16_bf16 v[16:31], v[240:243], v[80:83], v[16:31]
	s_waitcnt lgkmcnt(0)
	v_mfma_f32_32x32x16_bf16 v[0:15], v[248:251], v[80:83], v[0:15]
	s_cmp_lg_u32 s14, s23
	s_cbranch_scc1 .LBB0_556
	ds_bpermute_b32 v64, v183, v164
	s_lshl_b32 s54, s21, 1
	v_lshlrev_b32_e32 v176, 3, v174
	s_waitcnt vmcnt(0) lgkmcnt(0)
	s_barrier
	v_add_f32_e32 v64, v164, v64
	v_div_scale_f32 v65, s[0:1], v64, v64, 1.0
	v_rcp_f32_e32 v66, v65
	v_div_scale_f32 v67, vcc, 1.0, v64, 1.0
	v_fma_f32 v68, -v65, v66, 1.0
	v_fmac_f32_e32 v66, v68, v66
	v_mul_f32_e32 v68, v67, v66
	v_fma_f32 v69, -v65, v68, v67
	v_fmac_f32_e32 v68, v69, v66
	v_fma_f32 v65, -v65, v68, v67
	v_div_fmas_f32 v65, v65, v66, v68
	v_mov_b64_e32 v[66:67], s[12:13]
	v_div_fixup_f32 v64, v65, v64, 1.0
	v_mad_i64_i32 v[66:67], s[0:1], v175, s78, v[66:67]
	v_lshl_add_u64 v[66:67], v[66:67], 0, s[54:55]
	v_pk_mul_f32 v[48:49], v[48:49], v[64:65] op_sel_hi:[1,0]
	v_pk_mul_f32 v[50:51], v[50:51], v[64:65] op_sel_hi:[1,0]
	v_pk_mul_f32 v[32:33], v[32:33], v[64:65] op_sel_hi:[1,0]
	v_pk_mul_f32 v[34:35], v[34:35], v[64:65] op_sel_hi:[1,0]
	v_pk_mul_f32 v[16:17], v[16:17], v[64:65] op_sel_hi:[1,0]
	v_pk_mul_f32 v[18:19], v[18:19], v[64:65] op_sel_hi:[1,0]
	v_pk_mul_f32 v[0:1], v[0:1], v[64:65] op_sel_hi:[1,0]
	v_pk_mul_f32 v[2:3], v[2:3], v[64:65] op_sel_hi:[1,0]
	v_lshl_add_u64 v[66:67], v[66:67], 0, v[176:177]
	v_cvt_pk_bf16_f32 v48, v48, v49
	v_cvt_pk_bf16_f32 v49, v50, v51
	v_cvt_pk_bf16_f32 v32, v32, v33
	v_cvt_pk_bf16_f32 v33, v34, v35
	v_cvt_pk_bf16_f32 v16, v16, v17
	v_cvt_pk_bf16_f32 v17, v18, v19
	v_cvt_pk_bf16_f32 v0, v0, v1
	v_cvt_pk_bf16_f32 v1, v2, v3
	global_store_dwordx2 v[66:67], v[48:49], off
	v_pk_mul_f32 v[48:49], v[52:53], v[64:65] op_sel_hi:[1,0]
	v_pk_mul_f32 v[50:51], v[54:55], v[64:65] op_sel_hi:[1,0]
	global_store_dwordx2 v[66:67], v[32:33], off offset:64
	v_pk_mul_f32 v[32:33], v[36:37], v[64:65] op_sel_hi:[1,0]
	v_pk_mul_f32 v[34:35], v[38:39], v[64:65] op_sel_hi:[1,0]
	global_store_dwordx2 v[66:67], v[16:17], off offset:128
	v_pk_mul_f32 v[16:17], v[20:21], v[64:65] op_sel_hi:[1,0]
	v_pk_mul_f32 v[18:19], v[22:23], v[64:65] op_sel_hi:[1,0]
	global_store_dwordx2 v[66:67], v[0:1], off offset:192
	v_pk_mul_f32 v[0:1], v[4:5], v[64:65] op_sel_hi:[1,0]
	v_pk_mul_f32 v[2:3], v[6:7], v[64:65] op_sel_hi:[1,0]
	v_cvt_pk_bf16_f32 v48, v48, v49
	v_cvt_pk_bf16_f32 v49, v50, v51
	v_cvt_pk_bf16_f32 v32, v32, v33
	v_cvt_pk_bf16_f32 v33, v34, v35
	v_cvt_pk_bf16_f32 v16, v16, v17
	v_cvt_pk_bf16_f32 v17, v18, v19
	v_cvt_pk_bf16_f32 v0, v0, v1
	v_cvt_pk_bf16_f32 v1, v2, v3
	global_store_dwordx2 v[66:67], v[48:49], off offset:16
	v_pk_mul_f32 v[48:49], v[56:57], v[64:65] op_sel_hi:[1,0]
	v_pk_mul_f32 v[50:51], v[58:59], v[64:65] op_sel_hi:[1,0]
	global_store_dwordx2 v[66:67], v[32:33], off offset:80
	v_pk_mul_f32 v[32:33], v[40:41], v[64:65] op_sel_hi:[1,0]
	v_pk_mul_f32 v[34:35], v[42:43], v[64:65] op_sel_hi:[1,0]
	global_store_dwordx2 v[66:67], v[16:17], off offset:144
	v_pk_mul_f32 v[16:17], v[24:25], v[64:65] op_sel_hi:[1,0]
	v_pk_mul_f32 v[18:19], v[26:27], v[64:65] op_sel_hi:[1,0]
	global_store_dwordx2 v[66:67], v[0:1], off offset:208
	v_pk_mul_f32 v[0:1], v[8:9], v[64:65] op_sel_hi:[1,0]
	v_pk_mul_f32 v[2:3], v[10:11], v[64:65] op_sel_hi:[1,0]
	v_cvt_pk_bf16_f32 v48, v48, v49
	v_cvt_pk_bf16_f32 v49, v50, v51
	v_cvt_pk_bf16_f32 v32, v32, v33
	v_cvt_pk_bf16_f32 v33, v34, v35
	v_cvt_pk_bf16_f32 v16, v16, v17
	v_cvt_pk_bf16_f32 v17, v18, v19
	v_cvt_pk_bf16_f32 v0, v0, v1
	v_cvt_pk_bf16_f32 v1, v2, v3
	global_store_dwordx2 v[66:67], v[48:49], off offset:32
	v_pk_mul_f32 v[48:49], v[60:61], v[64:65] op_sel_hi:[1,0]
	v_pk_mul_f32 v[50:51], v[62:63], v[64:65] op_sel_hi:[1,0]
	global_store_dwordx2 v[66:67], v[32:33], off offset:96
	v_pk_mul_f32 v[32:33], v[44:45], v[64:65] op_sel_hi:[1,0]
	v_pk_mul_f32 v[34:35], v[46:47], v[64:65] op_sel_hi:[1,0]
	global_store_dwordx2 v[66:67], v[16:17], off offset:160
	v_pk_mul_f32 v[16:17], v[28:29], v[64:65] op_sel_hi:[1,0]
	v_pk_mul_f32 v[18:19], v[30:31], v[64:65] op_sel_hi:[1,0]
	global_store_dwordx2 v[66:67], v[0:1], off offset:224
	v_pk_mul_f32 v[0:1], v[12:13], v[64:65] op_sel_hi:[1,0]
	v_pk_mul_f32 v[2:3], v[14:15], v[64:65] op_sel_hi:[1,0]
	s_add_i32 s20, s20, s36
	s_add_i32 s11, s11, s36
	v_cvt_pk_bf16_f32 v48, v48, v49
	v_cvt_pk_bf16_f32 v49, v50, v51
	v_cvt_pk_bf16_f32 v32, v32, v33
	v_cvt_pk_bf16_f32 v33, v34, v35
	v_cvt_pk_bf16_f32 v16, v16, v17
	v_cvt_pk_bf16_f32 v17, v18, v19
	v_cvt_pk_bf16_f32 v0, v0, v1
	v_cvt_pk_bf16_f32 v1, v2, v3
	s_cmp_ge_i32 s20, s10
	global_store_dwordx2 v[66:67], v[48:49], off offset:48
	global_store_dwordx2 v[66:67], v[32:33], off offset:112
	global_store_dwordx2 v[66:67], v[16:17], off offset:176
	global_store_dwordx2 v[66:67], v[0:1], off offset:240
	s_cbranch_scc0 .LBB0_541
